# gate-GEMM epilogue (acc * max(sigmoid gate,1e-30) -> bf16): 16 serialized load-wait-store rounds rewritten with all 16 loads issued up front and counted vmcnt waits
# baseline (speedup 1.0000x reference)
; __device__ __forceinline__ float bf_lo(unsigned w) { return __uint_as_float(w << 16); }
; __device__ __forceinline__ float bf_hi(unsigned w) { return __uint_as_float(w & 0xffff0000u); }
;     static __device__ __forceinline__ u32x4 pack8(const f32x4 a, const f32x4 b) { u32x4 w; w.x = cvtpk(a[0], a[1]); w.y = cvtpk(a[2], a[3]); w.z = cvtpk(b[0], b[1]); w.w = cvtpk(b[2], b[3]); return w; }
;     __device__ __forceinline__ void operator()(const f32x4 (&acc)[2][2][4][2], const pg8::Unit& u, int wr, int wc, int fr_, int fq_) const {
;     ...
;         } else if (MEN(6)) {
;             const bf16_t* G = (const bf16_t*)i0; bf16_t* mg = (bf16_t*)o0;
; #pragma unroll
;             for (int ai = 0; ai < 2; ++ai)
; #pragma unroll
;                 for (int m = 0; m < 4; ++m) {
;                     const int row = rowbase + ai * 128 + m * 16 + fr;
; #pragma unroll
;                     for (int bj = 0; bj < 2; ++bj) {
;                         const size_t off = (size_t)row * DM + u.pn * 256 + bj * 128 + cw;
;                         const u32x4 g = *(const u32x4*)(G + off);
;                         f32x4 a = acc[ai][bj][m][0], b = acc[ai][bj][m][1];
;                         a[0] *= fmaxf(bf_lo(g.x), 1e-30f); a[1] *= fmaxf(bf_hi(g.x), 1e-30f); a[2] *= fmaxf(bf_lo(g.y), 1e-30f); a[3] *= fmaxf(bf_hi(g.y), 1e-30f);
;                         b[0] *= fmaxf(bf_lo(g.z), 1e-30f); b[1] *= fmaxf(bf_hi(g.z), 1e-30f); b[2] *= fmaxf(bf_lo(g.w), 1e-30f); b[3] *= fmaxf(bf_hi(g.w), 1e-30f);
;                         if (mode == M_GATE2) {
;                             const u32x4 p = *(const u32x4*)(mg + off);
;                             a[0] += bf_lo(p.x); a[1] += bf_hi(p.x); a[2] += bf_lo(p.y); a[3] += bf_hi(p.y);
;                             b[0] += bf_lo(p.z); b[1] += bf_hi(p.z); b[2] += bf_lo(p.w); b[3] += bf_hi(p.w);
;                         }
;                         *(u32x4*)(mg + off) = pack8(a, b);
;                     }
;                 }
.LBB0_402:
	v_mov_b32_e32 v193, v189
	v_mov_b32_e32 v195, v187
	s_cmp_lt_i32 s67, 3
	v_lshlrev_b32_e32 v140, 3, v195
	v_lshl_add_u32 v194, v195, 4, v193
	v_add_u32_e32 v2, s57, v140
	s_mov_b64 s[6:7], -1
	s_cbranch_scc1 .LBB0_463
	s_cmp_lt_i32 s67, 4
	s_cbranch_scc1 .LBB0_457
	s_cmp_lt_i32 s67, 5
	s_cbranch_scc1 .LBB0_416
	s_cmp_lg_u32 s67, 5
	s_cbranch_scc0 .LBB0_407
	v_add_u32_e32 v132, s2, v193
	v_add_u32_e32 v133, s92, v2
	v_lshlrev_b32_e32 v133, 1, v133
	v_lshl_add_u32 v132, v132, 11, v133
	s_mov_b64 s[6:7], 0
	global_load_dwordx4 v[160:163], v132, s[4:5]
	v_add_u32_e32 v133, 0x100, v132
	global_load_dwordx4 v[164:167], v133, s[4:5]
	v_add_u32_e32 v133, 0x8000, v132
	global_load_dwordx4 v[168:171], v133, s[4:5]
	v_add_u32_e32 v133, 0x8100, v132
	global_load_dwordx4 v[172:175], v133, s[4:5]
	v_add_u32_e32 v133, 0x10000, v132
	global_load_dwordx4 v[176:179], v133, s[4:5]
	v_add_u32_e32 v133, 0x10100, v132
	global_load_dwordx4 v[180:183], v133, s[4:5]
	v_add_u32_e32 v133, 0x18000, v132
	global_load_dwordx4 v[194:197], v133, s[4:5]
	v_add_u32_e32 v133, 0x18100, v132
	global_load_dwordx4 v[198:201], v133, s[4:5]
	v_add_u32_e32 v133, 0x40000, v132
	global_load_dwordx4 v[202:205], v133, s[4:5]
	v_add_u32_e32 v133, 0x40100, v132
	global_load_dwordx4 v[206:209], v133, s[4:5]
	v_add_u32_e32 v133, 0x48000, v132
	global_load_dwordx4 v[210:213], v133, s[4:5]
	v_add_u32_e32 v133, 0x48100, v132
	global_load_dwordx4 v[236:239], v133, s[4:5]
	v_add_u32_e32 v133, 0x50000, v132
	global_load_dwordx4 v[240:243], v133, s[4:5]
	v_add_u32_e32 v133, 0x50100, v132
	global_load_dwordx4 v[244:247], v133, s[4:5]
	v_add_u32_e32 v133, 0x58000, v132
	global_load_dwordx4 v[248:251], v133, s[4:5]
	v_add_u32_e32 v133, 0x58100, v132
	global_load_dwordx4 v[136:139], v133, s[4:5]
	s_waitcnt vmcnt(15)
	v_lshlrev_b32_e32 v134, 16, v160
	v_and_b32_e32 v135, 0xffff0000, v160
	v_max_f32_e32 v134, 0xda24260, v134
	v_max_f32_e32 v135, 0xda24260, v135
	v_lshlrev_b32_e32 v140, 16, v161
	v_and_b32_e32 v141, 0xffff0000, v161
	v_max_f32_e32 v140, 0xda24260, v140
	v_max_f32_e32 v141, 0xda24260, v141
	v_lshlrev_b32_e32 v142, 16, v162
	v_and_b32_e32 v143, 0xffff0000, v162
	v_max_f32_e32 v142, 0xda24260, v142
	v_max_f32_e32 v143, 0xda24260, v143
	v_lshlrev_b32_e32 v144, 16, v163
	v_and_b32_e32 v145, 0xffff0000, v163
	v_max_f32_e32 v144, 0xda24260, v144
	v_max_f32_e32 v145, 0xda24260, v145
	v_pk_mul_f32 v[134:135], v[124:125], v[134:135]
	v_pk_mul_f32 v[140:141], v[126:127], v[140:141]
	v_pk_mul_f32 v[142:143], v[116:117], v[142:143]
	v_pk_mul_f32 v[144:145], v[118:119], v[144:145]
	v_cvt_pk_bf16_f32 v160, v134, v135
	v_cvt_pk_bf16_f32 v161, v140, v141
	v_cvt_pk_bf16_f32 v162, v142, v143
	v_cvt_pk_bf16_f32 v163, v144, v145
	global_store_dwordx4 v132, v[160:163], s[96:97]
	s_waitcnt vmcnt(15)
	v_lshlrev_b32_e32 v134, 16, v164
	v_and_b32_e32 v135, 0xffff0000, v164
	v_max_f32_e32 v134, 0xda24260, v134
	v_max_f32_e32 v135, 0xda24260, v135
	v_lshlrev_b32_e32 v140, 16, v165
	v_and_b32_e32 v141, 0xffff0000, v165
	v_max_f32_e32 v140, 0xda24260, v140
	v_max_f32_e32 v141, 0xda24260, v141
	v_lshlrev_b32_e32 v142, 16, v166
	v_and_b32_e32 v143, 0xffff0000, v166
	v_max_f32_e32 v142, 0xda24260, v142
	v_max_f32_e32 v143, 0xda24260, v143
	v_lshlrev_b32_e32 v144, 16, v167
	v_and_b32_e32 v145, 0xffff0000, v167
	v_max_f32_e32 v144, 0xda24260, v144
	v_max_f32_e32 v145, 0xda24260, v145
	v_pk_mul_f32 v[134:135], v[128:129], v[134:135]
	v_pk_mul_f32 v[140:141], v[130:131], v[140:141]
	v_pk_mul_f32 v[142:143], v[120:121], v[142:143]
	v_pk_mul_f32 v[144:145], v[122:123], v[144:145]
	v_cvt_pk_bf16_f32 v164, v134, v135
	v_cvt_pk_bf16_f32 v165, v140, v141
	v_cvt_pk_bf16_f32 v166, v142, v143
	v_cvt_pk_bf16_f32 v167, v144, v145
	v_add_u32_e32 v133, 0x100, v132
	global_store_dwordx4 v133, v[164:167], s[96:97]
	s_waitcnt vmcnt(15)
	v_lshlrev_b32_e32 v134, 16, v168
	v_and_b32_e32 v135, 0xffff0000, v168
	v_max_f32_e32 v134, 0xda24260, v134
	v_max_f32_e32 v135, 0xda24260, v135
	v_lshlrev_b32_e32 v140, 16, v169
	v_and_b32_e32 v141, 0xffff0000, v169
	v_max_f32_e32 v140, 0xda24260, v140
	v_max_f32_e32 v141, 0xda24260, v141
	v_lshlrev_b32_e32 v142, 16, v170
	v_and_b32_e32 v143, 0xffff0000, v170
	v_max_f32_e32 v142, 0xda24260, v142
	v_max_f32_e32 v143, 0xda24260, v143
	v_lshlrev_b32_e32 v144, 16, v171
	v_and_b32_e32 v145, 0xffff0000, v171
	v_max_f32_e32 v144, 0xda24260, v144
	v_max_f32_e32 v145, 0xda24260, v145
	v_pk_mul_f32 v[134:135], v[108:109], v[134:135]
	v_pk_mul_f32 v[140:141], v[110:111], v[140:141]
	v_pk_mul_f32 v[142:143], v[100:101], v[142:143]
	v_pk_mul_f32 v[144:145], v[102:103], v[144:145]
	v_cvt_pk_bf16_f32 v168, v134, v135
	v_cvt_pk_bf16_f32 v169, v140, v141
	v_cvt_pk_bf16_f32 v170, v142, v143
	v_cvt_pk_bf16_f32 v171, v144, v145
	v_add_u32_e32 v133, 0x8000, v132
	global_store_dwordx4 v133, v[168:171], s[96:97]
	s_waitcnt vmcnt(15)
	v_lshlrev_b32_e32 v134, 16, v172
	v_and_b32_e32 v135, 0xffff0000, v172
	v_max_f32_e32 v134, 0xda24260, v134
	v_max_f32_e32 v135, 0xda24260, v135
	v_lshlrev_b32_e32 v140, 16, v173
	v_and_b32_e32 v141, 0xffff0000, v173
	v_max_f32_e32 v140, 0xda24260, v140
	v_max_f32_e32 v141, 0xda24260, v141
	v_lshlrev_b32_e32 v142, 16, v174
	v_and_b32_e32 v143, 0xffff0000, v174
	v_max_f32_e32 v142, 0xda24260, v142
	v_max_f32_e32 v143, 0xda24260, v143
	v_lshlrev_b32_e32 v144, 16, v175
	v_and_b32_e32 v145, 0xffff0000, v175
	v_max_f32_e32 v144, 0xda24260, v144
	v_max_f32_e32 v145, 0xda24260, v145
	v_pk_mul_f32 v[134:135], v[112:113], v[134:135]
	v_pk_mul_f32 v[140:141], v[114:115], v[140:141]
	v_pk_mul_f32 v[142:143], v[104:105], v[142:143]
	v_pk_mul_f32 v[144:145], v[106:107], v[144:145]
	v_cvt_pk_bf16_f32 v172, v134, v135
	v_cvt_pk_bf16_f32 v173, v140, v141
	v_cvt_pk_bf16_f32 v174, v142, v143
	v_cvt_pk_bf16_f32 v175, v144, v145
	v_add_u32_e32 v133, 0x8100, v132
	global_store_dwordx4 v133, v[172:175], s[96:97]
	s_waitcnt vmcnt(15)
; __device__ __forceinline__ float bf_lo(unsigned w) { return __uint_as_float(w << 16); }
; __device__ __forceinline__ float bf_hi(unsigned w) { return __uint_as_float(w & 0xffff0000u); }
;     static __device__ __forceinline__ u32x4 pack8(const f32x4 a, const f32x4 b) { u32x4 w; w.x = cvtpk(a[0], a[1]); w.y = cvtpk(a[2], a[3]); w.z = cvtpk(b[0], b[1]); w.w = cvtpk(b[2], b[3]); return w; }
;     __device__ __forceinline__ void operator()(const f32x4 (&acc)[2][2][4][2], const pg8::Unit& u, int wr, int wc, int fr_, int fq_) const {
;     ...
;         } else if (MEN(6)) {
;             const bf16_t* G = (const bf16_t*)i0; bf16_t* mg = (bf16_t*)o0;
; #pragma unroll
;             for (int ai = 0; ai < 2; ++ai)
; #pragma unroll
;                 for (int m = 0; m < 4; ++m) {
;                     const int row = rowbase + ai * 128 + m * 16 + fr;
; #pragma unroll
;                     for (int bj = 0; bj < 2; ++bj) {
;                         const size_t off = (size_t)row * DM + u.pn * 256 + bj * 128 + cw;
;                         const u32x4 g = *(const u32x4*)(G + off);
;                         f32x4 a = acc[ai][bj][m][0], b = acc[ai][bj][m][1];
;                         a[0] *= fmaxf(bf_lo(g.x), 1e-30f); a[1] *= fmaxf(bf_hi(g.x), 1e-30f); a[2] *= fmaxf(bf_lo(g.y), 1e-30f); a[3] *= fmaxf(bf_hi(g.y), 1e-30f);
;                         b[0] *= fmaxf(bf_lo(g.z), 1e-30f); b[1] *= fmaxf(bf_hi(g.z), 1e-30f); b[2] *= fmaxf(bf_lo(g.w), 1e-30f); b[3] *= fmaxf(bf_hi(g.w), 1e-30f);
;                         if (mode == M_GATE2) {
;                             const u32x4 p = *(const u32x4*)(mg + off);
;                             a[0] += bf_lo(p.x); a[1] += bf_hi(p.x); a[2] += bf_lo(p.y); a[3] += bf_hi(p.y);
;                             b[0] += bf_lo(p.z); b[1] += bf_hi(p.z); b[2] += bf_lo(p.w); b[3] += bf_hi(p.w);
;                         }
;                         *(u32x4*)(mg + off) = pack8(a, b);
;                     }
;                 }
	v_lshlrev_b32_e32 v134, 16, v176
	v_and_b32_e32 v135, 0xffff0000, v176
	v_max_f32_e32 v134, 0xda24260, v134
	v_max_f32_e32 v135, 0xda24260, v135
	v_lshlrev_b32_e32 v140, 16, v177
	v_and_b32_e32 v141, 0xffff0000, v177
	v_max_f32_e32 v140, 0xda24260, v140
	v_max_f32_e32 v141, 0xda24260, v141
	v_lshlrev_b32_e32 v142, 16, v178
	v_and_b32_e32 v143, 0xffff0000, v178
	v_max_f32_e32 v142, 0xda24260, v142
	v_max_f32_e32 v143, 0xda24260, v143
	v_lshlrev_b32_e32 v144, 16, v179
	v_and_b32_e32 v145, 0xffff0000, v179
	v_max_f32_e32 v144, 0xda24260, v144
	v_max_f32_e32 v145, 0xda24260, v145
	v_pk_mul_f32 v[134:135], v[92:93], v[134:135]
	v_pk_mul_f32 v[140:141], v[94:95], v[140:141]
	v_pk_mul_f32 v[142:143], v[84:85], v[142:143]
	v_pk_mul_f32 v[144:145], v[86:87], v[144:145]
	v_cvt_pk_bf16_f32 v176, v134, v135
	v_cvt_pk_bf16_f32 v177, v140, v141
	v_cvt_pk_bf16_f32 v178, v142, v143
	v_cvt_pk_bf16_f32 v179, v144, v145
	v_add_u32_e32 v133, 0x10000, v132
	global_store_dwordx4 v133, v[176:179], s[96:97]
	s_waitcnt vmcnt(15)
	v_lshlrev_b32_e32 v134, 16, v180
	v_and_b32_e32 v135, 0xffff0000, v180
	v_max_f32_e32 v134, 0xda24260, v134
	v_max_f32_e32 v135, 0xda24260, v135
	v_lshlrev_b32_e32 v140, 16, v181
	v_and_b32_e32 v141, 0xffff0000, v181
	v_max_f32_e32 v140, 0xda24260, v140
	v_max_f32_e32 v141, 0xda24260, v141
	v_lshlrev_b32_e32 v142, 16, v182
	v_and_b32_e32 v143, 0xffff0000, v182
	v_max_f32_e32 v142, 0xda24260, v142
	v_max_f32_e32 v143, 0xda24260, v143
	v_lshlrev_b32_e32 v144, 16, v183
	v_and_b32_e32 v145, 0xffff0000, v183
	v_max_f32_e32 v144, 0xda24260, v144
	v_max_f32_e32 v145, 0xda24260, v145
	v_pk_mul_f32 v[134:135], v[96:97], v[134:135]
	v_pk_mul_f32 v[140:141], v[98:99], v[140:141]
	v_pk_mul_f32 v[142:143], v[88:89], v[142:143]
	v_pk_mul_f32 v[144:145], v[90:91], v[144:145]
	v_cvt_pk_bf16_f32 v180, v134, v135
	v_cvt_pk_bf16_f32 v181, v140, v141
	v_cvt_pk_bf16_f32 v182, v142, v143
	v_cvt_pk_bf16_f32 v183, v144, v145
	v_add_u32_e32 v133, 0x10100, v132
	global_store_dwordx4 v133, v[180:183], s[96:97]
	s_waitcnt vmcnt(15)
	v_lshlrev_b32_e32 v134, 16, v194
	v_and_b32_e32 v135, 0xffff0000, v194
	v_max_f32_e32 v134, 0xda24260, v134
	v_max_f32_e32 v135, 0xda24260, v135
	v_lshlrev_b32_e32 v140, 16, v195
	v_and_b32_e32 v141, 0xffff0000, v195
	v_max_f32_e32 v140, 0xda24260, v140
	v_max_f32_e32 v141, 0xda24260, v141
	v_lshlrev_b32_e32 v142, 16, v196
	v_and_b32_e32 v143, 0xffff0000, v196
	v_max_f32_e32 v142, 0xda24260, v142
	v_max_f32_e32 v143, 0xda24260, v143
	v_lshlrev_b32_e32 v144, 16, v197
	v_and_b32_e32 v145, 0xffff0000, v197
	v_max_f32_e32 v144, 0xda24260, v144
	v_max_f32_e32 v145, 0xda24260, v145
	v_pk_mul_f32 v[134:135], v[76:77], v[134:135]
	v_pk_mul_f32 v[140:141], v[78:79], v[140:141]
	v_pk_mul_f32 v[142:143], v[68:69], v[142:143]
	v_pk_mul_f32 v[144:145], v[70:71], v[144:145]
	v_cvt_pk_bf16_f32 v194, v134, v135
	v_cvt_pk_bf16_f32 v195, v140, v141
	v_cvt_pk_bf16_f32 v196, v142, v143
	v_cvt_pk_bf16_f32 v197, v144, v145
	v_add_u32_e32 v133, 0x18000, v132
	global_store_dwordx4 v133, v[194:197], s[96:97]
	s_waitcnt vmcnt(15)
	v_lshlrev_b32_e32 v134, 16, v198
	v_and_b32_e32 v135, 0xffff0000, v198
	v_max_f32_e32 v134, 0xda24260, v134
	v_max_f32_e32 v135, 0xda24260, v135
	v_lshlrev_b32_e32 v140, 16, v199
	v_and_b32_e32 v141, 0xffff0000, v199
	v_max_f32_e32 v140, 0xda24260, v140
	v_max_f32_e32 v141, 0xda24260, v141
	v_lshlrev_b32_e32 v142, 16, v200
	v_and_b32_e32 v143, 0xffff0000, v200
	v_max_f32_e32 v142, 0xda24260, v142
	v_max_f32_e32 v143, 0xda24260, v143
	v_lshlrev_b32_e32 v144, 16, v201
	v_and_b32_e32 v145, 0xffff0000, v201
	v_max_f32_e32 v144, 0xda24260, v144
	v_max_f32_e32 v145, 0xda24260, v145
	v_pk_mul_f32 v[134:135], v[80:81], v[134:135]
	v_pk_mul_f32 v[140:141], v[82:83], v[140:141]
	v_pk_mul_f32 v[142:143], v[72:73], v[142:143]
	v_pk_mul_f32 v[144:145], v[74:75], v[144:145]
	v_cvt_pk_bf16_f32 v198, v134, v135
	v_cvt_pk_bf16_f32 v199, v140, v141
	v_cvt_pk_bf16_f32 v200, v142, v143
	v_cvt_pk_bf16_f32 v201, v144, v145
	v_add_u32_e32 v133, 0x18100, v132
	global_store_dwordx4 v133, v[198:201], s[96:97]
	s_waitcnt vmcnt(15)
	v_lshlrev_b32_e32 v134, 16, v202
	v_and_b32_e32 v135, 0xffff0000, v202
	v_max_f32_e32 v134, 0xda24260, v134
	v_max_f32_e32 v135, 0xda24260, v135
	v_lshlrev_b32_e32 v140, 16, v203
	v_and_b32_e32 v141, 0xffff0000, v203
	v_max_f32_e32 v140, 0xda24260, v140
	v_max_f32_e32 v141, 0xda24260, v141
	v_lshlrev_b32_e32 v142, 16, v204
	v_and_b32_e32 v143, 0xffff0000, v204
	v_max_f32_e32 v142, 0xda24260, v142
	v_max_f32_e32 v143, 0xda24260, v143
	v_lshlrev_b32_e32 v144, 16, v205
	v_and_b32_e32 v145, 0xffff0000, v205
	v_max_f32_e32 v144, 0xda24260, v144
	v_max_f32_e32 v145, 0xda24260, v145
	v_pk_mul_f32 v[134:135], v[60:61], v[134:135]
	v_pk_mul_f32 v[140:141], v[62:63], v[140:141]
	v_pk_mul_f32 v[142:143], v[52:53], v[142:143]
	v_pk_mul_f32 v[144:145], v[54:55], v[144:145]
	v_cvt_pk_bf16_f32 v202, v134, v135
	v_cvt_pk_bf16_f32 v203, v140, v141
	v_cvt_pk_bf16_f32 v204, v142, v143
	v_cvt_pk_bf16_f32 v205, v144, v145
	v_add_u32_e32 v133, 0x40000, v132
	global_store_dwordx4 v133, v[202:205], s[96:97]
	s_waitcnt vmcnt(15)
	v_lshlrev_b32_e32 v134, 16, v206
	v_and_b32_e32 v135, 0xffff0000, v206
	v_max_f32_e32 v134, 0xda24260, v134
	v_max_f32_e32 v135, 0xda24260, v135
	v_lshlrev_b32_e32 v140, 16, v207
	v_and_b32_e32 v141, 0xffff0000, v207
	v_max_f32_e32 v140, 0xda24260, v140
	v_max_f32_e32 v141, 0xda24260, v141
	v_lshlrev_b32_e32 v142, 16, v208
	v_and_b32_e32 v143, 0xffff0000, v208
	v_max_f32_e32 v142, 0xda24260, v142
	v_max_f32_e32 v143, 0xda24260, v143
	v_lshlrev_b32_e32 v144, 16, v209
	v_and_b32_e32 v145, 0xffff0000, v209
	v_max_f32_e32 v144, 0xda24260, v144
	v_max_f32_e32 v145, 0xda24260, v145
	v_pk_mul_f32 v[134:135], v[64:65], v[134:135]
	v_pk_mul_f32 v[140:141], v[66:67], v[140:141]
	v_pk_mul_f32 v[142:143], v[56:57], v[142:143]
	v_pk_mul_f32 v[144:145], v[58:59], v[144:145]
	v_cvt_pk_bf16_f32 v206, v134, v135
	v_cvt_pk_bf16_f32 v207, v140, v141
	v_cvt_pk_bf16_f32 v208, v142, v143
	v_cvt_pk_bf16_f32 v209, v144, v145
	v_add_u32_e32 v133, 0x40100, v132
	global_store_dwordx4 v133, v[206:209], s[96:97]
	s_waitcnt vmcnt(15)
; __device__ __forceinline__ float bf_lo(unsigned w) { return __uint_as_float(w << 16); }
; __device__ __forceinline__ float bf_hi(unsigned w) { return __uint_as_float(w & 0xffff0000u); }
;     static __device__ __forceinline__ u32x4 pack8(const f32x4 a, const f32x4 b) { u32x4 w; w.x = cvtpk(a[0], a[1]); w.y = cvtpk(a[2], a[3]); w.z = cvtpk(b[0], b[1]); w.w = cvtpk(b[2], b[3]); return w; }
;     __device__ __forceinline__ void operator()(const f32x4 (&acc)[2][2][4][2], const pg8::Unit& u, int wr, int wc, int fr_, int fq_) const {
;     ...
;         } else if (MEN(6)) {
;             const bf16_t* G = (const bf16_t*)i0; bf16_t* mg = (bf16_t*)o0;
; #pragma unroll
;             for (int ai = 0; ai < 2; ++ai)
; #pragma unroll
;                 for (int m = 0; m < 4; ++m) {
;                     const int row = rowbase + ai * 128 + m * 16 + fr;
; #pragma unroll
;                     for (int bj = 0; bj < 2; ++bj) {
;                         const size_t off = (size_t)row * DM + u.pn * 256 + bj * 128 + cw;
;                         const u32x4 g = *(const u32x4*)(G + off);
;                         f32x4 a = acc[ai][bj][m][0], b = acc[ai][bj][m][1];
;                         a[0] *= fmaxf(bf_lo(g.x), 1e-30f); a[1] *= fmaxf(bf_hi(g.x), 1e-30f); a[2] *= fmaxf(bf_lo(g.y), 1e-30f); a[3] *= fmaxf(bf_hi(g.y), 1e-30f);
;                         b[0] *= fmaxf(bf_lo(g.z), 1e-30f); b[1] *= fmaxf(bf_hi(g.z), 1e-30f); b[2] *= fmaxf(bf_lo(g.w), 1e-30f); b[3] *= fmaxf(bf_hi(g.w), 1e-30f);
;                         if (mode == M_GATE2) {
;                             const u32x4 p = *(const u32x4*)(mg + off);
;                             a[0] += bf_lo(p.x); a[1] += bf_hi(p.x); a[2] += bf_lo(p.y); a[3] += bf_hi(p.y);
;                             b[0] += bf_lo(p.z); b[1] += bf_hi(p.z); b[2] += bf_lo(p.w); b[3] += bf_hi(p.w);
;                         }
;                         *(u32x4*)(mg + off) = pack8(a, b);
;                     }
;                 }
	v_lshlrev_b32_e32 v134, 16, v210
	v_and_b32_e32 v135, 0xffff0000, v210
	v_max_f32_e32 v134, 0xda24260, v134
	v_max_f32_e32 v135, 0xda24260, v135
	v_lshlrev_b32_e32 v140, 16, v211
	v_and_b32_e32 v141, 0xffff0000, v211
	v_max_f32_e32 v140, 0xda24260, v140
	v_max_f32_e32 v141, 0xda24260, v141
	v_lshlrev_b32_e32 v142, 16, v212
	v_and_b32_e32 v143, 0xffff0000, v212
	v_max_f32_e32 v142, 0xda24260, v142
	v_max_f32_e32 v143, 0xda24260, v143
	v_lshlrev_b32_e32 v144, 16, v213
	v_and_b32_e32 v145, 0xffff0000, v213
	v_max_f32_e32 v144, 0xda24260, v144
	v_max_f32_e32 v145, 0xda24260, v145
	v_pk_mul_f32 v[134:135], v[44:45], v[134:135]
	v_pk_mul_f32 v[140:141], v[46:47], v[140:141]
	v_pk_mul_f32 v[142:143], v[36:37], v[142:143]
	v_pk_mul_f32 v[144:145], v[38:39], v[144:145]
	v_cvt_pk_bf16_f32 v210, v134, v135
	v_cvt_pk_bf16_f32 v211, v140, v141
	v_cvt_pk_bf16_f32 v212, v142, v143
	v_cvt_pk_bf16_f32 v213, v144, v145
	v_add_u32_e32 v133, 0x48000, v132
	global_store_dwordx4 v133, v[210:213], s[96:97]
	s_waitcnt vmcnt(15)
	v_lshlrev_b32_e32 v134, 16, v236
	v_and_b32_e32 v135, 0xffff0000, v236
	v_max_f32_e32 v134, 0xda24260, v134
	v_max_f32_e32 v135, 0xda24260, v135
	v_lshlrev_b32_e32 v140, 16, v237
	v_and_b32_e32 v141, 0xffff0000, v237
	v_max_f32_e32 v140, 0xda24260, v140
	v_max_f32_e32 v141, 0xda24260, v141
	v_lshlrev_b32_e32 v142, 16, v238
	v_and_b32_e32 v143, 0xffff0000, v238
	v_max_f32_e32 v142, 0xda24260, v142
	v_max_f32_e32 v143, 0xda24260, v143
	v_lshlrev_b32_e32 v144, 16, v239
	v_and_b32_e32 v145, 0xffff0000, v239
	v_max_f32_e32 v144, 0xda24260, v144
	v_max_f32_e32 v145, 0xda24260, v145
	v_pk_mul_f32 v[134:135], v[48:49], v[134:135]
	v_pk_mul_f32 v[140:141], v[50:51], v[140:141]
	v_pk_mul_f32 v[142:143], v[40:41], v[142:143]
	v_pk_mul_f32 v[144:145], v[42:43], v[144:145]
	v_cvt_pk_bf16_f32 v236, v134, v135
	v_cvt_pk_bf16_f32 v237, v140, v141
	v_cvt_pk_bf16_f32 v238, v142, v143
	v_cvt_pk_bf16_f32 v239, v144, v145
	v_add_u32_e32 v133, 0x48100, v132
	global_store_dwordx4 v133, v[236:239], s[96:97]
	s_waitcnt vmcnt(15)
	v_lshlrev_b32_e32 v134, 16, v240
	v_and_b32_e32 v135, 0xffff0000, v240
	v_max_f32_e32 v134, 0xda24260, v134
	v_max_f32_e32 v135, 0xda24260, v135
	v_lshlrev_b32_e32 v140, 16, v241
	v_and_b32_e32 v141, 0xffff0000, v241
	v_max_f32_e32 v140, 0xda24260, v140
	v_max_f32_e32 v141, 0xda24260, v141
	v_lshlrev_b32_e32 v142, 16, v242
	v_and_b32_e32 v143, 0xffff0000, v242
	v_max_f32_e32 v142, 0xda24260, v142
	v_max_f32_e32 v143, 0xda24260, v143
	v_lshlrev_b32_e32 v144, 16, v243
	v_and_b32_e32 v145, 0xffff0000, v243
	v_max_f32_e32 v144, 0xda24260, v144
	v_max_f32_e32 v145, 0xda24260, v145
	v_pk_mul_f32 v[134:135], v[28:29], v[134:135]
	v_pk_mul_f32 v[140:141], v[30:31], v[140:141]
	v_pk_mul_f32 v[142:143], v[20:21], v[142:143]
	v_pk_mul_f32 v[144:145], v[22:23], v[144:145]
	v_cvt_pk_bf16_f32 v240, v134, v135
	v_cvt_pk_bf16_f32 v241, v140, v141
	v_cvt_pk_bf16_f32 v242, v142, v143
	v_cvt_pk_bf16_f32 v243, v144, v145
	v_add_u32_e32 v133, 0x50000, v132
	global_store_dwordx4 v133, v[240:243], s[96:97]
	s_waitcnt vmcnt(15)
	v_lshlrev_b32_e32 v134, 16, v244
	v_and_b32_e32 v135, 0xffff0000, v244
	v_max_f32_e32 v134, 0xda24260, v134
	v_max_f32_e32 v135, 0xda24260, v135
	v_lshlrev_b32_e32 v140, 16, v245
	v_and_b32_e32 v141, 0xffff0000, v245
	v_max_f32_e32 v140, 0xda24260, v140
	v_max_f32_e32 v141, 0xda24260, v141
	v_lshlrev_b32_e32 v142, 16, v246
	v_and_b32_e32 v143, 0xffff0000, v246
	v_max_f32_e32 v142, 0xda24260, v142
	v_max_f32_e32 v143, 0xda24260, v143
	v_lshlrev_b32_e32 v144, 16, v247
	v_and_b32_e32 v145, 0xffff0000, v247
	v_max_f32_e32 v144, 0xda24260, v144
	v_max_f32_e32 v145, 0xda24260, v145
	v_pk_mul_f32 v[134:135], v[32:33], v[134:135]
	v_pk_mul_f32 v[140:141], v[34:35], v[140:141]
	v_pk_mul_f32 v[142:143], v[24:25], v[142:143]
	v_pk_mul_f32 v[144:145], v[26:27], v[144:145]
	v_cvt_pk_bf16_f32 v244, v134, v135
	v_cvt_pk_bf16_f32 v245, v140, v141
	v_cvt_pk_bf16_f32 v246, v142, v143
	v_cvt_pk_bf16_f32 v247, v144, v145
	v_add_u32_e32 v133, 0x50100, v132
	global_store_dwordx4 v133, v[244:247], s[96:97]
	s_waitcnt vmcnt(15)
	v_lshlrev_b32_e32 v134, 16, v248
	v_and_b32_e32 v135, 0xffff0000, v248
	v_max_f32_e32 v134, 0xda24260, v134
	v_max_f32_e32 v135, 0xda24260, v135
	v_lshlrev_b32_e32 v140, 16, v249
	v_and_b32_e32 v141, 0xffff0000, v249
	v_max_f32_e32 v140, 0xda24260, v140
	v_max_f32_e32 v141, 0xda24260, v141
	v_lshlrev_b32_e32 v142, 16, v250
	v_and_b32_e32 v143, 0xffff0000, v250
	v_max_f32_e32 v142, 0xda24260, v142
	v_max_f32_e32 v143, 0xda24260, v143
	v_lshlrev_b32_e32 v144, 16, v251
	v_and_b32_e32 v145, 0xffff0000, v251
	v_max_f32_e32 v144, 0xda24260, v144
	v_max_f32_e32 v145, 0xda24260, v145
	v_pk_mul_f32 v[134:135], v[12:13], v[134:135]
	v_pk_mul_f32 v[140:141], v[14:15], v[140:141]
	v_pk_mul_f32 v[142:143], v[4:5], v[142:143]
	v_pk_mul_f32 v[144:145], v[6:7], v[144:145]
	v_cvt_pk_bf16_f32 v248, v134, v135
	v_cvt_pk_bf16_f32 v249, v140, v141
	v_cvt_pk_bf16_f32 v250, v142, v143
	v_cvt_pk_bf16_f32 v251, v144, v145
	v_add_u32_e32 v133, 0x58000, v132
	global_store_dwordx4 v133, v[248:251], s[96:97]
	s_waitcnt vmcnt(15)
	v_lshlrev_b32_e32 v134, 16, v136
	v_and_b32_e32 v135, 0xffff0000, v136
	v_max_f32_e32 v134, 0xda24260, v134
	v_max_f32_e32 v135, 0xda24260, v135
	v_lshlrev_b32_e32 v140, 16, v137
	v_and_b32_e32 v141, 0xffff0000, v137
	v_max_f32_e32 v140, 0xda24260, v140
	v_max_f32_e32 v141, 0xda24260, v141
	v_lshlrev_b32_e32 v142, 16, v138
	v_and_b32_e32 v143, 0xffff0000, v138
	v_max_f32_e32 v142, 0xda24260, v142
	v_max_f32_e32 v143, 0xda24260, v143
	v_lshlrev_b32_e32 v144, 16, v139
	v_and_b32_e32 v145, 0xffff0000, v139
	v_max_f32_e32 v144, 0xda24260, v144
	v_max_f32_e32 v145, 0xda24260, v145
	v_pk_mul_f32 v[134:135], v[16:17], v[134:135]
	v_pk_mul_f32 v[140:141], v[18:19], v[140:141]
	v_pk_mul_f32 v[142:143], v[8:9], v[142:143]
	v_pk_mul_f32 v[144:145], v[10:11], v[144:145]
	v_cvt_pk_bf16_f32 v136, v134, v135
	v_cvt_pk_bf16_f32 v137, v140, v141
	v_cvt_pk_bf16_f32 v138, v142, v143
	v_cvt_pk_bf16_f32 v139, v144, v145
	v_add_u32_e32 v133, 0x58100, v132
	global_store_dwordx4 v133, v[136:139], s[96:97]
